# attention softmax: lane^32 max/sum exchanges via v_permlane32_swap instead of ds_bpermute round trips
# baseline (speedup 1.0000x reference)
; DI float shx(float v, int m, int lane) { return __int_as_float(__builtin_amdgcn_ds_bpermute((lane ^ m) << 2, __float_as_int(v))); }
; DI void attn_item(const bf16_t* P, bf16_t* Y, const float* sinkp, const float* rope, unsigned char* lds, bool is_ctx, int b, int blk, int hp) {
;     ...
;             if (mask != 1) {
;                 int dq = qi0 + 16 * t - fq * 4; float negbig = -1e30f; asm volatile("" : "+v"(dq), "+v"(negbig));
;                 if (mask == 2) dq = -dq;
; #pragma unroll
;                 for (int kt = 0; kt < 8; ++kt)
; #pragma unroll
;                     for (int j = 0; j < 4; ++j) { const int kk = kt * 16 + j; const bool ok = (mask == 0) ? (kk >= dq) : (-kk >= dq); if (!ok) S[t][kt][j] = negbig; }
;             }
;             float mx = -1e30f;
; #pragma unroll
;             for (int kt = 0; kt < 8; ++kt)
; #pragma unroll
;                 for (int j = 0; j < 4; ++j) mx = fmaxf(mx, S[t][kt][j]);
;             mx = fmaxf(mx, shx(mx, 16, lane)); mx = fmaxf(mx, shx(mx, 32, lane));
;             const float m_new = fmaxf(m_run[t], mx);
;             const float alpha = __builtin_amdgcn_exp2f(m_run[t] - m_new);
;             f32x4 sum4 = (f32x4){0.f, 0.f, 0.f, 0.f};
; #pragma unroll
;             for (int kt = 0; kt < 8; ++kt) {
;                 const f32x4 dv = S[t][kt] - m_new;
;                 f32x4 ev; ev[0] = __builtin_amdgcn_exp2f(dv[0]); ev[1] = __builtin_amdgcn_exp2f(dv[1]); ev[2] = __builtin_amdgcn_exp2f(dv[2]); ev[3] = __builtin_amdgcn_exp2f(dv[3]);
;                 S[t][kt] = ev; sum4 += ev;
;             }
;             float sum = (sum4[0] + sum4[1]) + (sum4[2] + sum4[3]);
;             sum += shx(sum, 16, lane); sum += shx(sum, 32, lane);
;             l_run[t] = l_run[t] * alpha + sum; m_run[t] = m_new;
.LBB0_496:
	s_nop 3
	v_max3_f32 v154, v142, s36, v143
	v_max3_f32 v154, v154, v144, v145
	v_max3_f32 v154, v154, v138, v139
	v_max3_f32 v154, v154, v140, v141
	v_max3_f32 v154, v154, v134, v135
	v_max3_f32 v154, v154, v136, v137
	v_max3_f32 v154, v154, v130, v131
	v_max3_f32 v154, v154, v132, v133
	v_max3_f32 v154, v154, v126, v127
	v_max3_f32 v154, v154, v128, v129
	v_max3_f32 v154, v154, v122, v123
	v_max3_f32 v154, v154, v124, v125
	v_max3_f32 v154, v154, v118, v119
	v_max3_f32 v154, v154, v120, v121
	v_max3_f32 v154, v154, v114, v115
	v_max3_f32 v154, v154, v116, v117
	ds_bpermute_b32 v155, v174, v154
	s_andn2_b64 vcc, exec, s[48:49]
	s_waitcnt lgkmcnt(0)
	v_max_f32_e32 v155, v155, v155
	v_max_f32_e32 v154, v154, v155
	v_mov_b32_e32 v155, v154
	s_nop 1
	v_permlane32_swap_b32_e32 v155, v154
	s_waitcnt lgkmcnt(0)
	v_max3_f32 v192, v163, v154, v155
	v_sub_f32_e32 v145, v145, v192
	v_sub_f32_e32 v144, v144, v192
	v_sub_f32_e32 v143, v143, v192
	v_sub_f32_e32 v142, v142, v192
	v_sub_f32_e32 v141, v141, v192
	v_sub_f32_e32 v140, v140, v192
	v_exp_f32_e32 v154, v142
	v_exp_f32_e32 v155, v143
	v_exp_f32_e32 v156, v144
	v_exp_f32_e32 v157, v145
	v_sub_f32_e32 v139, v139, v192
	v_sub_f32_e32 v138, v138, v192
	v_exp_f32_e32 v158, v138
	v_exp_f32_e32 v160, v140
	v_exp_f32_e32 v161, v141
	v_exp_f32_e32 v159, v139
	v_pk_add_f32 v[138:139], v[154:155], 0 op_sel_hi:[1,0]
	v_pk_add_f32 v[140:141], v[156:157], 0 op_sel_hi:[1,0]
	v_sub_f32_e32 v137, v137, v192
	v_sub_f32_e32 v136, v136, v192
	v_sub_f32_e32 v135, v135, v192
	v_sub_f32_e32 v134, v134, v192
	v_pk_add_f32 v[166:167], v[160:161], v[140:141]
	v_pk_add_f32 v[168:169], v[158:159], v[138:139]
	v_exp_f32_e32 v138, v134
	v_exp_f32_e32 v139, v135
	v_exp_f32_e32 v140, v136
	v_exp_f32_e32 v141, v137
	v_sub_f32_e32 v133, v133, v192
	v_sub_f32_e32 v132, v132, v192
	v_sub_f32_e32 v131, v131, v192
	v_sub_f32_e32 v130, v130, v192
	v_exp_f32_e32 v142, v130
	v_exp_f32_e32 v144, v132
	v_exp_f32_e32 v145, v133
	v_exp_f32_e32 v143, v131
	v_pk_add_f32 v[130:131], v[138:139], v[168:169]
	v_pk_add_f32 v[132:133], v[140:141], v[166:167]
	v_sub_f32_e32 v129, v129, v192
	v_sub_f32_e32 v128, v128, v192
	v_sub_f32_e32 v127, v127, v192
	v_sub_f32_e32 v126, v126, v192
	v_pk_add_f32 v[166:167], v[144:145], v[132:133]
	v_pk_add_f32 v[168:169], v[142:143], v[130:131]
	v_exp_f32_e32 v130, v126
	v_exp_f32_e32 v131, v127
	v_exp_f32_e32 v132, v128
	v_exp_f32_e32 v133, v129
	v_sub_f32_e32 v125, v125, v192
	v_sub_f32_e32 v124, v124, v192
	v_sub_f32_e32 v123, v123, v192
	v_sub_f32_e32 v122, v122, v192
	v_exp_f32_e32 v134, v122
	v_exp_f32_e32 v136, v124
	v_exp_f32_e32 v137, v125
	v_exp_f32_e32 v135, v123
	v_pk_add_f32 v[122:123], v[130:131], v[168:169]
	v_pk_add_f32 v[124:125], v[132:133], v[166:167]
	v_sub_f32_e32 v121, v121, v192
	v_sub_f32_e32 v120, v120, v192
	v_sub_f32_e32 v119, v119, v192
	v_sub_f32_e32 v118, v118, v192
	v_pk_add_f32 v[166:167], v[136:137], v[124:125]
	v_pk_add_f32 v[168:169], v[134:135], v[122:123]
	v_exp_f32_e32 v122, v118
	v_exp_f32_e32 v123, v119
	v_exp_f32_e32 v124, v120
	v_exp_f32_e32 v125, v121
	v_sub_f32_e32 v117, v117, v192
	v_sub_f32_e32 v116, v116, v192
	v_sub_f32_e32 v115, v115, v192
	v_sub_f32_e32 v114, v114, v192
	v_exp_f32_e32 v126, v114
	v_exp_f32_e32 v128, v116
	v_exp_f32_e32 v129, v117
	v_exp_f32_e32 v127, v115
	v_pk_add_f32 v[114:115], v[122:123], v[168:169]
	v_pk_add_f32 v[116:117], v[124:125], v[166:167]
	v_pk_add_f32 v[114:115], v[126:127], v[114:115]
	v_pk_add_f32 v[116:117], v[128:129], v[116:117]
	v_add_f32_e32 v114, v114, v115
	v_add_f32_e32 v115, v116, v117
	v_add_f32_e32 v114, v114, v115
	ds_bpermute_b32 v115, v174, v114
	s_waitcnt lgkmcnt(0)
	v_add_f32_e32 v114, v114, v115
	v_mov_b32_e32 v115, v114
	s_nop 1
	v_permlane32_swap_b32_e32 v115, v114
	s_cbranch_vccnz .LBB0_498
	v_mov_b32_e32 v116, v187
	v_mov_b32_e32 v117, 0xf149f2ca
	s_and_b64 s[6:7], s[46:47], exec
	v_sub_u32_e32 v118, 0, v116
	v_cndmask_b32_e64 v116, v116, v118, s[42:43]
	v_cmp_lt_i32_e32 vcc, 0, v116
	s_cselect_b32 s6, 1, -1
	s_nop 0
	v_cndmask_b32_e32 v110, v110, v117, vcc
	v_cmp_lt_i32_e32 vcc, s6, v116
	s_cselect_b32 s6, 2, -2
	s_nop 0
	v_cndmask_b32_e32 v111, v111, v117, vcc
	v_cmp_lt_i32_e32 vcc, s6, v116
	s_cselect_b32 s6, 3, -3
	s_nop 0
	v_cndmask_b32_e32 v112, v112, v117, vcc
	v_cmp_lt_i32_e32 vcc, s6, v116
	s_cselect_b32 s6, 16, -16
	s_nop 0
	v_cndmask_b32_e32 v113, v113, v117, vcc
	v_cmp_lt_i32_e32 vcc, s6, v116
	s_cselect_b32 s6, 17, 0xffffffef
	s_nop 0
	v_cndmask_b32_e32 v106, v106, v117, vcc
	v_cmp_lt_i32_e32 vcc, s6, v116
	s_cselect_b32 s6, 18, 0xffffffee
	s_nop 0
	v_cndmask_b32_e32 v107, v107, v117, vcc
	v_cmp_lt_i32_e32 vcc, s6, v116
	s_cselect_b32 s6, 19, 0xffffffed
	s_nop 0
	v_cndmask_b32_e32 v108, v108, v117, vcc
	v_cmp_lt_i32_e32 vcc, s6, v116
	s_cselect_b32 s6, 32, 0xffffffe0
	s_nop 0
	v_cndmask_b32_e32 v109, v109, v117, vcc
	v_cmp_lt_i32_e32 vcc, s6, v116
	s_cselect_b32 s6, 33, 0xffffffdf
	s_nop 0
	v_cndmask_b32_e32 v82, v82, v117, vcc
	v_cmp_lt_i32_e32 vcc, s6, v116
	s_cselect_b32 s6, 34, 0xffffffde
	s_nop 0
	v_cndmask_b32_e32 v83, v83, v117, vcc
	v_cmp_lt_i32_e32 vcc, s6, v116
	s_cselect_b32 s6, 35, 0xffffffdd
	s_nop 0
	v_cndmask_b32_e32 v84, v84, v117, vcc
	v_cmp_lt_i32_e32 vcc, s6, v116
	s_cselect_b32 s6, 48, 0xffffffd0
	s_nop 0
	v_cndmask_b32_e32 v85, v85, v117, vcc
	v_cmp_lt_i32_e32 vcc, s6, v116
	s_cselect_b32 s6, 49, 0xffffffcf
	s_nop 0
	v_cndmask_b32_e32 v86, v86, v117, vcc
	v_cmp_lt_i32_e32 vcc, s6, v116
	s_cselect_b32 s6, 50, 0xffffffce
	s_nop 0
	v_cndmask_b32_e32 v87, v87, v117, vcc
	v_cmp_lt_i32_e32 vcc, s6, v116
	s_cselect_b32 s6, 51, 0xffffffcd
	s_nop 0
	v_cndmask_b32_e32 v88, v88, v117, vcc
; DI float shx(float v, int m, int lane) { return __int_as_float(__builtin_amdgcn_ds_bpermute((lane ^ m) << 2, __float_as_int(v))); }
; DI void attn_item(const bf16_t* P, bf16_t* Y, const float* sinkp, const float* rope, unsigned char* lds, bool is_ctx, int b, int blk, int hp) {
;     ...
;             if (mask != 1) {
;                 int dq = qi0 + 16 * t - fq * 4; float negbig = -1e30f; asm volatile("" : "+v"(dq), "+v"(negbig));
;                 if (mask == 2) dq = -dq;
; #pragma unroll
;                 for (int kt = 0; kt < 8; ++kt)
; #pragma unroll
;                     for (int j = 0; j < 4; ++j) { const int kk = kt * 16 + j; const bool ok = (mask == 0) ? (kk >= dq) : (-kk >= dq); if (!ok) S[t][kt][j] = negbig; }
;             }
;             float mx = -1e30f;
; #pragma unroll
;             for (int kt = 0; kt < 8; ++kt)
; #pragma unroll
;                 for (int j = 0; j < 4; ++j) mx = fmaxf(mx, S[t][kt][j]);
;             mx = fmaxf(mx, shx(mx, 16, lane)); mx = fmaxf(mx, shx(mx, 32, lane));
;             const float m_new = fmaxf(m_run[t], mx);
;             const float alpha = __builtin_amdgcn_exp2f(m_run[t] - m_new);
;             f32x4 sum4 = (f32x4){0.f, 0.f, 0.f, 0.f};
; #pragma unroll
;             for (int kt = 0; kt < 8; ++kt) {
;                 const f32x4 dv = S[t][kt] - m_new;
;                 f32x4 ev; ev[0] = __builtin_amdgcn_exp2f(dv[0]); ev[1] = __builtin_amdgcn_exp2f(dv[1]); ev[2] = __builtin_amdgcn_exp2f(dv[2]); ev[3] = __builtin_amdgcn_exp2f(dv[3]);
;                 S[t][kt] = ev; sum4 += ev;
;             }
;             float sum = (sum4[0] + sum4[1]) + (sum4[2] + sum4[3]);
;             sum += shx(sum, 16, lane); sum += shx(sum, 32, lane);
;             l_run[t] = l_run[t] * alpha + sum; m_run[t] = m_new;
; #pragma unroll
;             for (int dt = 0; dt < 4; ++dt) O[t][dt] *= alpha;
;         }
	v_cmp_lt_i32_e32 vcc, s6, v116
	s_cselect_b32 s6, 64, 0xffffffc0
	s_nop 0
	v_cndmask_b32_e32 v89, v89, v117, vcc
	v_cmp_lt_i32_e32 vcc, s6, v116
	s_cselect_b32 s6, s87, 0xffffffbf
	s_nop 0
	v_cndmask_b32_e32 v90, v90, v117, vcc
	v_cmp_lt_i32_e32 vcc, s6, v116
	s_cselect_b32 s6, s88, 0xffffffbe
	s_nop 0
	v_cndmask_b32_e32 v91, v91, v117, vcc
	v_cmp_lt_i32_e32 vcc, s6, v116
	s_cselect_b32 s6, s89, 0xffffffbd
	s_nop 0
	v_cndmask_b32_e32 v92, v92, v117, vcc
	v_cmp_lt_i32_e32 vcc, s6, v116
	s_cselect_b32 s6, 0x50, s92
	s_nop 0
	v_cndmask_b32_e32 v93, v93, v117, vcc
	v_cmp_lt_i32_e32 vcc, s6, v116
	s_cselect_b32 s6, s93, 0xffffffaf
	s_nop 0
	v_cndmask_b32_e32 v98, v98, v117, vcc
	v_cmp_lt_i32_e32 vcc, s6, v116
	s_cselect_b32 s6, s97, 0xffffffae
	s_nop 0
	v_cndmask_b32_e32 v99, v99, v117, vcc
	v_cmp_lt_i32_e32 vcc, s6, v116
	s_cselect_b32 s6, s98, 0xffffffad
	s_nop 0
	v_cndmask_b32_e32 v100, v100, v117, vcc
	v_cmp_lt_i32_e32 vcc, s6, v116
	s_cselect_b32 s6, 0x60, s99
	s_nop 0
	v_cndmask_b32_e32 v101, v101, v117, vcc
	v_cmp_lt_i32_e32 vcc, s6, v116
	s_cselect_b32 s6, s70, 0xffffff9f
	s_nop 0
	v_cndmask_b32_e32 v94, v94, v117, vcc
	v_cmp_lt_i32_e32 vcc, s6, v116
	s_cselect_b32 s6, s37, 0xffffff9e
	s_nop 0
	v_cndmask_b32_e32 v95, v95, v117, vcc
	v_cmp_lt_i32_e32 vcc, s6, v116
	s_cselect_b32 s6, s50, 0xffffff9d
	s_nop 0
	v_cndmask_b32_e32 v96, v96, v117, vcc
	v_cmp_lt_i32_e32 vcc, s6, v116
	s_cselect_b32 s6, s51, 0xffffff90
	s_nop 0
	v_cndmask_b32_e32 v97, v97, v117, vcc
	v_cmp_lt_i32_e32 vcc, s6, v116
	s_cselect_b32 s6, s26, 0xffffff8f
	s_nop 0
	v_cndmask_b32_e32 v102, v102, v117, vcc
	v_cmp_lt_i32_e32 vcc, s6, v116
	s_cselect_b32 s6, s90, 0xffffff8e
	s_nop 0
	v_cndmask_b32_e32 v103, v103, v117, vcc
	v_cmp_lt_i32_e32 vcc, s6, v116
	s_cselect_b32 s6, s91, 0xffffff8d
	s_nop 0
	v_cndmask_b32_e32 v104, v104, v117, vcc
	v_cmp_lt_i32_e32 vcc, s6, v116
	s_nop 1
	v_cndmask_b32_e32 v105, v105, v117, vcc
.LBB0_498:
	v_sub_f32_e32 v116, v163, v192
	v_exp_f32_e32 v166, v116
	s_waitcnt lgkmcnt(0)
	v_add_f32_e32 v194, v114, v115
	s_add_i32 s35, s35, 1
	s_add_i32 s6, s2, s35
	v_pk_mul_f32 v[114:115], v[70:71], v[166:167] op_sel_hi:[1,0]
	v_pk_mul_f32 v[70:71], v[74:75], v[166:167] op_sel_hi:[1,0]
	v_max3_f32 v74, v110, s36, v111
	v_max3_f32 v74, v74, v112, v113
	v_max3_f32 v74, v74, v106, v107
	v_max3_f32 v74, v74, v108, v109
	v_max3_f32 v74, v74, v82, v83
	v_max3_f32 v74, v74, v84, v85
	v_max3_f32 v74, v74, v86, v87
	v_max3_f32 v74, v74, v88, v89
	v_max3_f32 v74, v74, v90, v91
	v_max3_f32 v74, v74, v92, v93
	v_max3_f32 v74, v74, v98, v99
	v_max3_f32 v74, v74, v100, v101
	v_max3_f32 v74, v74, v94, v95
	v_max3_f32 v74, v74, v96, v97
	v_max3_f32 v74, v74, v102, v103
	v_max3_f32 v74, v74, v104, v105
	ds_bpermute_b32 v75, v174, v74
	v_pk_mul_f32 v[116:117], v[72:73], v[166:167] op_sel_hi:[1,0]
	v_pk_mul_f32 v[72:73], v[76:77], v[166:167] op_sel_hi:[1,0]
	v_fmac_f32_e32 v194, v164, v166
	v_pk_mul_f32 v[120:121], v[68:69], v[166:167] op_sel_hi:[1,0]
	s_waitcnt lgkmcnt(0)
	v_max_f32_e32 v75, v75, v75
	v_max_f32_e32 v74, v74, v75
	v_mov_b32_e32 v75, v74
	s_nop 1
	v_permlane32_swap_b32_e32 v75, v74
	v_pk_mul_f32 v[118:119], v[66:67], v[166:167] op_sel_hi:[1,0]
	v_pk_mul_f32 v[68:69], v[80:81], v[166:167] op_sel_hi:[1,0]
	v_pk_mul_f32 v[66:67], v[78:79], v[166:167] op_sel_hi:[1,0]
	s_cmp_lt_u32 s6, s3
	s_waitcnt lgkmcnt(0)
	v_max3_f32 v195, v162, v74, v75
	v_sub_f32_e32 v74, v113, v195
	v_sub_f32_e32 v75, v112, v195
	v_sub_f32_e32 v76, v111, v195
	v_sub_f32_e32 v77, v110, v195
	v_sub_f32_e32 v179, v162, v195
	v_exp_f32_e32 v162, v77
	v_exp_f32_e32 v163, v76
	v_exp_f32_e32 v164, v75
	v_exp_f32_e32 v165, v74
	v_sub_f32_e32 v78, v109, v195
	v_sub_f32_e32 v79, v108, v195
	v_sub_f32_e32 v80, v107, v195
	v_sub_f32_e32 v81, v106, v195
	v_exp_f32_e32 v166, v81
	v_exp_f32_e32 v167, v80
	v_exp_f32_e32 v168, v79
	v_exp_f32_e32 v169, v78
	v_sub_f32_e32 v78, v85, v195
	v_sub_f32_e32 v79, v84, v195
	v_sub_f32_e32 v80, v83, v195
	v_sub_f32_e32 v81, v82, v195
	v_exp_f32_e32 v106, v81
	v_exp_f32_e32 v107, v80
	v_exp_f32_e32 v108, v79
	v_exp_f32_e32 v109, v78
	v_sub_f32_e32 v78, v89, v195
	v_sub_f32_e32 v79, v88, v195
	v_sub_f32_e32 v80, v87, v195
	v_sub_f32_e32 v81, v86, v195
	v_exp_f32_e32 v110, v81
	v_exp_f32_e32 v111, v80
	v_exp_f32_e32 v112, v79
	v_exp_f32_e32 v113, v78
	v_sub_f32_e32 v78, v93, v195
	v_sub_f32_e32 v79, v92, v195
	v_sub_f32_e32 v80, v91, v195
	v_sub_f32_e32 v81, v90, v195
	v_pk_add_f32 v[74:75], v[162:163], 0 op_sel_hi:[1,0]
	v_pk_add_f32 v[76:77], v[164:165], 0 op_sel_hi:[1,0]
	v_exp_f32_e32 v82, v81
	v_exp_f32_e32 v83, v80
	v_exp_f32_e32 v84, v79
	v_exp_f32_e32 v85, v78
	v_sub_f32_e32 v78, v101, v195
	v_sub_f32_e32 v79, v100, v195
	v_sub_f32_e32 v80, v99, v195
	v_sub_f32_e32 v81, v98, v195
	v_pk_add_f32 v[76:77], v[168:169], v[76:77]
	v_pk_add_f32 v[74:75], v[166:167], v[74:75]
	v_exp_f32_e32 v86, v81
	v_exp_f32_e32 v87, v80
	v_exp_f32_e32 v88, v79
	v_exp_f32_e32 v89, v78
	v_pk_add_f32 v[74:75], v[106:107], v[74:75]
	v_pk_add_f32 v[76:77], v[108:109], v[76:77]
	v_pk_add_f32 v[74:75], v[110:111], v[74:75]
	v_pk_add_f32 v[76:77], v[112:113], v[76:77]
	v_pk_add_f32 v[74:75], v[82:83], v[74:75]
	v_pk_add_f32 v[76:77], v[84:85], v[76:77]
	v_pk_add_f32 v[80:81], v[86:87], v[74:75]
	v_pk_add_f32 v[78:79], v[88:89], v[76:77]
	v_sub_f32_e32 v77, v97, v195
	v_sub_f32_e32 v76, v96, v195
	v_sub_f32_e32 v75, v95, v195
	v_sub_f32_e32 v74, v94, v195
	v_exp_f32_e32 v74, v74
	v_exp_f32_e32 v75, v75
	v_exp_f32_e32 v76, v76
	v_exp_f32_e32 v77, v77
	v_exp_f32_e32 v100, v179
	v_pk_add_f32 v[90:91], v[74:75], v[80:81]
	v_sub_f32_e32 v81, v105, v195
	v_pk_add_f32 v[92:93], v[76:77], v[78:79]
	v_sub_f32_e32 v80, v104, v195
	v_sub_f32_e32 v79, v103, v195
	v_sub_f32_e32 v78, v102, v195
	v_exp_f32_e32 v78, v78
	v_exp_f32_e32 v79, v79
	v_exp_f32_e32 v80, v80
	v_exp_f32_e32 v81, v81
	v_pk_mul_f32 v[98:99], v[56:57], v[100:101] op_sel_hi:[1,0]
	v_pk_add_f32 v[90:91], v[78:79], v[90:91]
	v_pk_mul_f32 v[96:97], v[54:55], v[100:101] op_sel_hi:[1,0]
	v_pk_add_f32 v[92:93], v[80:81], v[92:93]
	v_pk_mul_f32 v[64:65], v[64:65], v[100:101] op_sel_hi:[1,0]
	v_pk_mov_b32 v[94:95], v[90:91], v[92:93] op_sel:[1,0]
	v_mov_b32_e32 v91, v93
	v_pk_add_f32 v[90:91], v[94:95], v[90:91]
	v_pk_mul_f32 v[94:95], v[52:53], v[100:101] op_sel_hi:[1,0]
	v_add_f32_e32 v90, v90, v91
	ds_bpermute_b32 v91, v174, v90
	v_pk_mul_f32 v[92:93], v[50:51], v[100:101] op_sel_hi:[1,0]
	v_pk_mul_f32 v[62:63], v[62:63], v[100:101] op_sel_hi:[1,0]
	v_pk_mul_f32 v[52:53], v[60:61], v[100:101] op_sel_hi:[1,0]
	v_pk_mul_f32 v[50:51], v[58:59], v[100:101] op_sel_hi:[1,0]
	s_waitcnt lgkmcnt(0)
; #define LAS __attribute__((address_space(3)))
; DI unsigned pk_bf16(float lo, float hi) { unsigned r; asm("v_cvt_pk_bf16_f32 %0, %1, %2" : "=v"(r) : "v"(lo), "v"(hi)); return r; }
; DI float shx(float v, int m, int lane) { return __int_as_float(__builtin_amdgcn_ds_bpermute((lane ^ m) << 2, __float_as_int(v))); }
; DI void attn_item(const bf16_t* P, bf16_t* Y, const float* sinkp, const float* rope, unsigned char* lds, bool is_ctx, int b, int blk, int hp) {
;     ...
;             sum += shx(sum, 16, lane); sum += shx(sum, 32, lane);
;             l_run[t] = l_run[t] * alpha + sum; m_run[t] = m_new;
; #pragma unroll
;             for (int dt = 0; dt < 4; ++dt) O[t][dt] *= alpha;
;         }
; #pragma unroll
;         for (int i = 0; i < 4; ++i) {
;             bf16x8 Pf[2];
; #pragma unroll
;             for (int t = 0; t < 2; ++t) {
;                 u32x4 pw; pw[0] = pk_bf16(S[t][2 * i][0], S[t][2 * i][1]); pw[1] = pk_bf16(S[t][2 * i][2], S[t][2 * i][3]); pw[2] = pk_bf16(S[t][2 * i + 1][0], S[t][2 * i + 1][1]); pw[3] = pk_bf16(S[t][2 * i + 1][2], S[t][2 * i + 1][3]);
;                 Pf[t] = __builtin_bit_cast(bf16x8, pw);
;             }
; #pragma unroll
;             for (int dt = 0; dt < 4; ++dt) {
;                 const s16x4 lo = __builtin_amdgcn_ds_read_tr16_b64_v4i16((LAS s16x4*)(Vb + (32 * i + fq * 4 + (fr >> 2)) * 72 + dt * 16 + 4 * (fr & 3)));
;                 const s16x4 hi = __builtin_amdgcn_ds_read_tr16_b64_v4i16((LAS s16x4*)(Vb + (32 * i + 16 + fq * 4 + (fr >> 2)) * 72 + dt * 16 + 4 * (fr & 3)));
;                 const bf16x8 Vf = __builtin_shufflevector(lo, hi, 0, 1, 2, 3, 4, 5, 6, 7);
; #pragma unroll
;                 for (int t = 0; t < 2; ++t) O[t][dt] = __builtin_amdgcn_mfma_f32_16x16x32_bf16(Vf, Pf[t], O[t][dt], 0, 0, 0);
;             }
;         }
	v_add_f32_e32 v90, v90, v91
	v_mov_b32_e32 v91, v90
	s_nop 1
	v_permlane32_swap_b32_e32 v91, v90
	v_cvt_pk_bf16_f32 v58, v154, v155
	v_cvt_pk_bf16_f32 v59, v156, v157
	v_cvt_pk_bf16_f32 v60, v158, v159
	v_cvt_pk_bf16_f32 v61, v160, v161
	s_waitcnt lgkmcnt(0)
	v_add_f32_e32 v90, v90, v91
	v_add3_u32 v91, s31, v188, v191
	v_fmac_f32_e32 v90, v193, v100
	ds_read_b64_tr_b16 v[102:103], v91 offset:20736
	ds_read_b64_tr_b16 v[100:101], v91 offset:18432
	ds_read_b64_tr_b16 v[154:155], v91 offset:18464
	ds_read_b64_tr_b16 v[156:157], v91 offset:20768
	v_cvt_pk_bf16_f32 v54, v162, v163
	v_cvt_pk_bf16_f32 v55, v164, v165
	v_cvt_pk_bf16_f32 v56, v166, v167
	v_cvt_pk_bf16_f32 v57, v168, v169
	s_waitcnt lgkmcnt(0)
	v_mfma_f32_16x16x32_bf16 v[118:121], v[100:103], v[58:61], v[118:121]
	v_mfma_f32_16x16x32_bf16 v[92:95], v[100:103], v[54:57], v[92:95]
	v_mfma_f32_16x16x32_bf16 v[100:103], v[154:157], v[58:61], v[114:117]
	s_nop 2
	ds_read_b64_tr_b16 v[114:115], v91 offset:18496
	ds_read_b64_tr_b16 v[116:117], v91 offset:20800
	s_waitcnt lgkmcnt(0)
	v_mfma_f32_16x16x32_bf16 v[70:73], v[114:117], v[58:61], v[70:73]
	v_mfma_f32_16x16x32_bf16 v[62:65], v[114:117], v[54:57], v[62:65]
	ds_read_b64_tr_b16 v[114:115], v91 offset:18528
	ds_read_b64_tr_b16 v[116:117], v91 offset:20832
	s_waitcnt lgkmcnt(0)
	v_mfma_f32_16x16x32_bf16 v[58:61], v[114:117], v[58:61], v[66:69]
	v_cvt_pk_bf16_f32 v66, v106, v107
	ds_read_b64_tr_b16 v[104:105], v91 offset:23040
	ds_read_b64_tr_b16 v[106:107], v91 offset:25344
	v_cvt_pk_bf16_f32 v67, v108, v109
	v_mfma_f32_16x16x32_bf16 v[96:99], v[154:157], v[54:57], v[96:99]
	v_cvt_pk_bf16_f32 v68, v110, v111
	v_cvt_pk_bf16_f32 v69, v112, v113
	v_cvt_pk_bf16_f32 v112, v74, v75
	v_mfma_f32_16x16x32_bf16 v[50:53], v[114:117], v[54:57], v[50:53]
	v_cvt_pk_bf16_f32 v54, v138, v139
	v_cvt_pk_bf16_f32 v55, v140, v141
	v_cvt_pk_bf16_f32 v56, v142, v143
	v_cvt_pk_bf16_f32 v57, v144, v145
	s_waitcnt lgkmcnt(0)
	v_mfma_f32_16x16x32_bf16 v[92:95], v[104:107], v[66:69], v[92:95]
	v_cvt_pk_bf16_f32 v113, v76, v77
	v_cvt_pk_bf16_f32 v114, v78, v79
	v_cvt_pk_bf16_f32 v115, v80, v81
	v_mfma_f32_16x16x32_bf16 v[108:111], v[104:107], v[54:57], v[118:121]
	ds_read_b64_tr_b16 v[104:105], v91 offset:23072
	ds_read_b64_tr_b16 v[106:107], v91 offset:25376
	s_waitcnt lgkmcnt(0)
	v_mfma_f32_16x16x32_bf16 v[100:103], v[104:107], v[54:57], v[100:103]
	v_mfma_f32_16x16x32_bf16 v[96:99], v[104:107], v[66:69], v[96:99]
	ds_read_b64_tr_b16 v[104:105], v91 offset:23104
	ds_read_b64_tr_b16 v[106:107], v91 offset:25408
	s_waitcnt lgkmcnt(0)
	v_mfma_f32_16x16x32_bf16 v[70:73], v[104:107], v[54:57], v[70:73]
	v_mfma_f32_16x16x32_bf16 v[62:65], v[104:107], v[66:69], v[62:65]
	ds_read_b64_tr_b16 v[104:105], v91 offset:23136
	ds_read_b64_tr_b16 v[106:107], v91 offset:25440
	s_waitcnt lgkmcnt(0)
	v_mfma_f32_16x16x32_bf16 v[50:53], v[104:107], v[66:69], v[50:53]
	v_cvt_pk_bf16_f32 v66, v82, v83
	v_cvt_pk_bf16_f32 v67, v84, v85
	ds_read_b64_tr_b16 v[82:83], v91 offset:27648
	ds_read_b64_tr_b16 v[84:85], v91 offset:29952
	v_mfma_f32_16x16x32_bf16 v[54:57], v[104:107], v[54:57], v[58:61]
	v_cvt_pk_bf16_f32 v58, v130, v131
	v_cvt_pk_bf16_f32 v59, v132, v133
	v_cvt_pk_bf16_f32 v60, v134, v135
	v_cvt_pk_bf16_f32 v61, v136, v137
	v_cvt_pk_bf16_f32 v68, v86, v87
	v_cvt_pk_bf16_f32 v69, v88, v89
	s_waitcnt lgkmcnt(0)
	v_mfma_f32_16x16x32_bf16 v[86:89], v[82:85], v[58:61], v[108:111]
	v_cvt_pk_bf16_f32 v108, v122, v123
	v_cvt_pk_bf16_f32 v109, v124, v125
	v_cvt_pk_bf16_f32 v110, v126, v127
	v_mfma_f32_16x16x32_bf16 v[82:85], v[82:85], v[66:69], v[92:95]
	s_nop 2
	ds_read_b64_tr_b16 v[92:93], v91 offset:27680
	ds_read_b64_tr_b16 v[94:95], v91 offset:29984
	v_cvt_pk_bf16_f32 v111, v128, v129
	s_waitcnt lgkmcnt(0)
	v_mfma_f32_16x16x32_bf16 v[100:103], v[92:95], v[58:61], v[100:103]
	v_mfma_f32_16x16x32_bf16 v[92:95], v[92:95], v[66:69], v[96:99]
	s_nop 2
	ds_read_b64_tr_b16 v[96:97], v91 offset:27712
	ds_read_b64_tr_b16 v[98:99], v91 offset:30016
	s_waitcnt lgkmcnt(0)
	v_mfma_f32_16x16x32_bf16 v[104:107], v[96:99], v[58:61], v[70:73]
	s_nop 2
	ds_read_b64_tr_b16 v[70:71], v91 offset:27744
	ds_read_b64_tr_b16 v[72:73], v91 offset:30048
	v_mfma_f32_16x16x32_bf16 v[62:65], v[96:99], v[66:69], v[62:65]
	s_waitcnt lgkmcnt(0)
	v_mfma_f32_16x16x32_bf16 v[96:99], v[70:73], v[66:69], v[50:53]
	s_nop 2
	ds_read_b64_tr_b16 v[50:51], v91 offset:32256
	ds_read_b64_tr_b16 v[52:53], v91 offset:34560
	v_mfma_f32_16x16x32_bf16 v[58:61], v[70:73], v[58:61], v[54:57]
	s_nop 2
	ds_read_b64_tr_b16 v[54:55], v91 offset:32288
	ds_read_b64_tr_b16 v[56:57], v91 offset:34592
	ds_read_b64_tr_b16 v[78:79], v91 offset:32320
	ds_read_b64_tr_b16 v[80:81], v91 offset:34624
	s_waitcnt lgkmcnt(0)
	v_mfma_f32_16x16x32_bf16 v[66:69], v[50:53], v[108:111], v[86:89]
	v_mfma_f32_16x16x32_bf16 v[50:53], v[50:53], v[112:115], v[82:85]
	s_nop 2
	ds_read_b64_tr_b16 v[82:83], v91 offset:32352
	ds_read_b64_tr_b16 v[84:85], v91 offset:34656
	v_mfma_f32_16x16x32_bf16 v[70:73], v[54:57], v[108:111], v[100:103]
	v_mfma_f32_16x16x32_bf16 v[54:57], v[54:57], v[112:115], v[92:95]
	v_mfma_f32_16x16x32_bf16 v[74:77], v[78:81], v[108:111], v[104:107]
	v_mfma_f32_16x16x32_bf16 v[62:65], v[78:81], v[112:115], v[62:65]
	s_waitcnt lgkmcnt(0)
	v_mfma_f32_16x16x32_bf16 v[78:81], v[82:85], v[108:111], v[58:61]
	v_mfma_f32_16x16x32_bf16 v[58:61], v[82:85], v[112:115], v[96:99]
	s_cbranch_scc0 .LBB0_421
	v_mov_b32_e32 v162, v195
	v_mov_b32_e32 v163, v192
	v_mov_b32_e32 v193, v90
	v_mov_b32_e32 v164, v194
	s_branch .LBB0_486
